# far-path softmax in dilated attention: xor-32 max exchange via v_permlane32_swap instead of ds_bpermute + lgkmcnt(0)
# speedup vs baseline: 1.0312x; 1.0312x over previous
.LBB0_531:
	v_mul_f32_e32 v48, v132, v48
	v_mul_f32_e32 v56, v132, v56
	v_fmac_f32_e32 v48, v49, v133
	v_fmac_f32_e32 v56, v57, v133
	v_fmac_f32_e32 v48, v50, v138
	v_fmac_f32_e32 v56, v58, v138
	v_fmac_f32_e32 v48, v51, v139
	v_fmac_f32_e32 v56, v59, v139
	v_fmac_f32_e32 v48, v52, v140
	v_fmac_f32_e32 v56, v60, v140
	v_fmac_f32_e32 v48, v53, v141
	v_fmac_f32_e32 v56, v61, v141
	v_fmac_f32_e32 v48, v54, v142
	v_fmac_f32_e32 v56, v62, v142
	v_fmac_f32_e32 v48, v55, v143
	v_fmac_f32_e32 v56, v63, v143
	v_fmamk_f32 v48, v48, 0x3e38aa3b, v196
	v_fmamk_f32 v49, v56, 0x3e38aa3b, v196
	v_max_f32_e32 v50, v48, v49
	v_mov_b32_e32 v51, v50
	s_nop 1
	v_permlane32_swap_b32_e32 v50, v51
	v_max3_f32 v206, v205, v50, v51
	v_sub_f32_e32 v48, v48, v206
	v_sub_f32_e32 v49, v49, v206
	v_exp_f32_e32 v48, v48
	v_exp_f32_e32 v50, v49
	v_sub_f32_e32 v49, v205, v206
	v_exp_f32_e32 v128, v49
	v_pk_mul_f32 v[174:175], v[132:133], v[48:49] op_sel_hi:[1,0]
	v_pk_mul_f32 v[178:179], v[132:133], v[50:51] op_sel_hi:[1,0]
	v_pk_mul_f32 v[176:177], v[138:139], v[48:49] op_sel_hi:[1,0]
	v_pk_mul_f32 v[182:183], v[138:139], v[50:51] op_sel_hi:[1,0]
	v_pk_mul_f32 v[180:181], v[140:141], v[48:49] op_sel_hi:[1,0]
	v_pk_mul_f32 v[186:187], v[140:141], v[50:51] op_sel_hi:[1,0]
	v_pk_mul_f32 v[184:185], v[142:143], v[48:49] op_sel_hi:[1,0]
	v_pk_mul_f32 v[188:189], v[142:143], v[50:51] op_sel_hi:[1,0]
	v_add_f32_e32 v207, v48, v50
	v_cmp_eq_f32_e32 vcc, 1.0, v128
	s_cmp_eq_u64 vcc, exec
	s_cbranch_scc0 .LBB0_457
	s_branch .LBB0_458

.LBB0_541:
	v_mul_f32_e32 v32, v132, v32
	v_mul_f32_e32 v40, v132, v40
	v_fmac_f32_e32 v32, v33, v133
	v_fmac_f32_e32 v40, v41, v133
	v_fmac_f32_e32 v32, v34, v138
	v_fmac_f32_e32 v40, v42, v138
	v_fmac_f32_e32 v32, v35, v139
	v_fmac_f32_e32 v40, v43, v139
	v_fmac_f32_e32 v32, v36, v140
	v_fmac_f32_e32 v40, v44, v140
	v_fmac_f32_e32 v32, v37, v141
	v_fmac_f32_e32 v40, v45, v141
	v_fmac_f32_e32 v32, v38, v142
	v_fmac_f32_e32 v40, v46, v142
	v_fmac_f32_e32 v32, v39, v143
	v_fmac_f32_e32 v40, v47, v143
	v_fmamk_f32 v32, v32, 0x3e38aa3b, v196
	v_fmamk_f32 v33, v40, 0x3e38aa3b, v196
	v_max_f32_e32 v34, v32, v33
	v_mov_b32_e32 v35, v34
	s_nop 1
	v_permlane32_swap_b32_e32 v34, v35
	v_max3_f32 v205, v206, v34, v35
	v_sub_f32_e32 v32, v32, v205
	v_sub_f32_e32 v33, v33, v205
	v_exp_f32_e32 v32, v32
	v_exp_f32_e32 v34, v33
	v_sub_f32_e32 v33, v206, v205
	v_exp_f32_e32 v128, v33
	v_pk_mul_f32 v[40:41], v[140:141], v[32:33] op_sel_hi:[1,0]
	v_pk_mul_f32 v[36:37], v[132:133], v[34:35] op_sel_hi:[1,0]
	v_pk_mul_f32 v[38:39], v[138:139], v[34:35] op_sel_hi:[1,0]
	v_pk_mul_f32 v[42:43], v[140:141], v[34:35] op_sel_hi:[1,0]
	v_pk_mul_f32 v[44:45], v[142:143], v[32:33] op_sel_hi:[1,0]
	v_pk_mul_f32 v[46:47], v[142:143], v[34:35] op_sel_hi:[1,0]
	v_pk_mul_f32 v[174:175], v[132:133], v[32:33] op_sel_hi:[1,0]
	v_pk_mul_f32 v[176:177], v[138:139], v[32:33] op_sel_hi:[1,0]
	v_add_f32_e32 v207, v32, v34
	v_mov_b32_e32 v179, v40
	v_mov_b32_e32 v178, v41
	v_mov_b32_e32 v183, v44
	v_mov_b32_e32 v182, v45
	v_mov_b32_e32 v181, v36
	v_mov_b32_e32 v180, v37
	v_mov_b32_e32 v185, v38
	v_mov_b32_e32 v184, v39
	v_mov_b32_e32 v187, v42
	v_mov_b32_e32 v186, v43
	v_mov_b32_e32 v189, v46
	v_mov_b32_e32 v188, v47
	v_cmp_eq_f32_e32 vcc, 1.0, v128
	s_cmp_eq_u64 vcc, exec
	s_cbranch_scc0 .LBB0_466
	s_branch .LBB0_467

.LBB0_551:
	v_mul_f32_e32 v48, v132, v48
	v_mul_f32_e32 v56, v132, v56
	v_fmac_f32_e32 v48, v49, v133
	v_fmac_f32_e32 v56, v57, v133
	v_fmac_f32_e32 v48, v50, v138
	v_fmac_f32_e32 v56, v58, v138
	v_fmac_f32_e32 v48, v51, v139
	v_fmac_f32_e32 v56, v59, v139
	v_fmac_f32_e32 v48, v52, v140
	v_fmac_f32_e32 v56, v60, v140
	v_fmac_f32_e32 v48, v53, v141
	v_fmac_f32_e32 v56, v61, v141
	v_fmac_f32_e32 v48, v54, v142
	v_fmac_f32_e32 v56, v62, v142
	v_fmac_f32_e32 v48, v55, v143
	v_fmac_f32_e32 v56, v63, v143
	v_fmamk_f32 v48, v48, 0x3e38aa3b, v196
	v_fmamk_f32 v49, v56, 0x3e38aa3b, v196
	v_max_f32_e32 v50, v48, v49
	v_mov_b32_e32 v51, v50
	s_nop 1
	v_permlane32_swap_b32_e32 v50, v51
	v_max3_f32 v206, v205, v50, v51
	v_sub_f32_e32 v48, v48, v206
	v_sub_f32_e32 v49, v49, v206
	v_exp_f32_e32 v48, v48
	v_exp_f32_e32 v50, v49
	v_sub_f32_e32 v49, v205, v206
	v_exp_f32_e32 v128, v49
	v_pk_mul_f32 v[56:57], v[140:141], v[48:49] op_sel_hi:[1,0]
	v_pk_mul_f32 v[52:53], v[132:133], v[50:51] op_sel_hi:[1,0]
	v_pk_mul_f32 v[54:55], v[138:139], v[50:51] op_sel_hi:[1,0]
	v_pk_mul_f32 v[58:59], v[140:141], v[50:51] op_sel_hi:[1,0]
	v_pk_mul_f32 v[60:61], v[142:143], v[48:49] op_sel_hi:[1,0]
	v_pk_mul_f32 v[62:63], v[142:143], v[50:51] op_sel_hi:[1,0]
	v_pk_mul_f32 v[174:175], v[132:133], v[48:49] op_sel_hi:[1,0]
	v_pk_mul_f32 v[176:177], v[138:139], v[48:49] op_sel_hi:[1,0]
	v_add_f32_e32 v207, v48, v50
	v_mov_b32_e32 v179, v56
	v_mov_b32_e32 v178, v57
	v_mov_b32_e32 v183, v60
	v_mov_b32_e32 v182, v61
	v_mov_b32_e32 v181, v52
	v_mov_b32_e32 v180, v53
	v_mov_b32_e32 v185, v54
	v_mov_b32_e32 v184, v55
	v_mov_b32_e32 v187, v58
	v_mov_b32_e32 v186, v59
	v_mov_b32_e32 v189, v62
	v_mov_b32_e32 v188, v63
	v_cmp_eq_f32_e32 vcc, 1.0, v128
	s_cmp_eq_u64 vcc, exec
	s_cbranch_scc0 .LBB0_475
	s_branch .LBB0_476

.LBB0_561:
	v_mul_f32_e32 v32, v132, v32
	v_mul_f32_e32 v40, v132, v40
	v_fmac_f32_e32 v32, v33, v133
	v_fmac_f32_e32 v40, v41, v133
	v_fmac_f32_e32 v32, v34, v138
	v_fmac_f32_e32 v40, v42, v138
	v_fmac_f32_e32 v32, v35, v139
	v_fmac_f32_e32 v40, v43, v139
	v_fmac_f32_e32 v32, v36, v140
	v_fmac_f32_e32 v40, v44, v140
	v_fmac_f32_e32 v32, v37, v141
	v_fmac_f32_e32 v40, v45, v141
	v_fmac_f32_e32 v32, v38, v142
	v_fmac_f32_e32 v40, v46, v142
	v_fmac_f32_e32 v32, v39, v143
	v_fmac_f32_e32 v40, v47, v143
	v_fmamk_f32 v32, v32, 0x3e38aa3b, v196
	v_fmamk_f32 v33, v40, 0x3e38aa3b, v196
	v_max_f32_e32 v34, v32, v33
	v_mov_b32_e32 v35, v34
	s_nop 1
	v_permlane32_swap_b32_e32 v34, v35
	v_max3_f32 v205, v206, v34, v35
	v_sub_f32_e32 v32, v32, v205
	v_sub_f32_e32 v33, v33, v205
	v_exp_f32_e32 v32, v32
	v_exp_f32_e32 v34, v33
	v_sub_f32_e32 v33, v206, v205
	v_exp_f32_e32 v126, v33
	v_pk_mul_f32 v[40:41], v[140:141], v[32:33] op_sel_hi:[1,0]
	v_pk_mul_f32 v[36:37], v[132:133], v[34:35] op_sel_hi:[1,0]
	v_pk_mul_f32 v[38:39], v[138:139], v[34:35] op_sel_hi:[1,0]
	v_pk_mul_f32 v[42:43], v[140:141], v[34:35] op_sel_hi:[1,0]
	v_pk_mul_f32 v[44:45], v[142:143], v[32:33] op_sel_hi:[1,0]
	v_pk_mul_f32 v[46:47], v[142:143], v[34:35] op_sel_hi:[1,0]
	v_pk_mul_f32 v[112:113], v[132:133], v[32:33] op_sel_hi:[1,0]
	v_pk_mul_f32 v[114:115], v[138:139], v[32:33] op_sel_hi:[1,0]
	v_add_f32_e32 v127, v32, v34
	v_mov_b32_e32 v117, v40
	v_mov_b32_e32 v116, v41
	v_mov_b32_e32 v121, v44
	v_mov_b32_e32 v120, v45
	v_mov_b32_e32 v119, v36
	v_mov_b32_e32 v118, v37
	v_mov_b32_e32 v123, v38
	v_mov_b32_e32 v122, v39
	v_mov_b32_e32 v125, v42
	v_mov_b32_e32 v124, v43
	v_mov_b32_e32 v175, v46
	v_mov_b32_e32 v174, v47
	v_cmp_eq_f32_e32 vcc, 1.0, v126
	s_cmp_eq_u64 vcc, exec
	s_cbranch_scc0 .LBB0_482
	s_branch .LBB0_483
